# filtergen split into 768 half-items; GEMM_UP epilogue inputs (conv taps, row stats) prefetched before the K-loop, epilogue vmcnt(0) relaxed
# speedup vs baseline: 1.0070x; 1.0070x over previous
; #define LAS __attribute__((address_space(3)))
; #define G_WAIT_V(n) asm volatile("s_waitcnt vmcnt(" #n ")" ::: "memory")
; template <class Epi>
; __device__ __forceinline__ void gemm_phase(LAS unsigned char* lds, const bf16_t* Ag, const bf16_t* Btg, const int K, const Sched& S, const Epi& E, int wv) {
;     ...
;     Unit cur, nxt; int ui = 0;
;     if (!S.next(0, cur)) return;
;     f32x4 acc[2][2][4][2];
; #pragma unroll
;     for (int a = 0; a < 2; ++a)
; #pragma unroll
;         for (int b = 0; b < 2; ++b)
; #pragma unroll
;             for (int m = 0; m < 4; ++m)
; #pragma unroll
;                 for (int n = 0; n < 2; ++n) acc[a][b][m][n] = (f32x4){0.f, 0.f, 0.f, 0.f};
;     bf16x8 At[4][2], B0[2][2], B1[2][2];
;     const char* cA = (const char*)Ag + cur.arow * (long)rowb;
;     const char* cB0 = (const char*)Btg + (size_t)cur.b0 * rowb;
;     const char* cB1 = (const char*)Btg + (size_t)cur.b1 * rowb;
;     G_STAGE(G_SB(0, 0), cB0, voffB); G_STAGE(G_SA(0, 0), cA, voffA); G_STAGE(G_SB(0, 1), cB1, voffB); G_STAGE(G_SA(0, 1), cA + hstep, voffA);
;     if (wr == 1) G_BAR;
;     G_WAIT_V(4); G_BAR;
;     G_STAGE(G_SB(1, 0), cB0 + kstep, voffB); G_STAGE(G_SA(1, 0), cA + kstep, voffA); G_STAGE(G_SB(1, 1), cB1 + kstep, voffB);
;     G_WAIT_V(6); G_BAR;
;     for (;;) {
;         const bool has_next = S.next(ui + 1, nxt);
;         const char* nA = has_next ? (const char*)Ag + nxt.arow * (long)rowb : cA;
;         const char* nB0 = has_next ? (const char*)Btg + (size_t)nxt.b0 * rowb : cB0;
;         const char* nB1 = has_next ? (const char*)Btg + (size_t)nxt.b1 * rowb : cB1;
;     __device__ __forceinline__ void operator()(f32x4 (&acc)[2][2][4][2], const Unit& u, int wr, int wc, int fr, int fq, LAS unsigned char* lds) const {
;     ...
;         int sb, L, i2; if (u.pm < 65) { sb = 0; L = LP; i2 = u.pm; } else { const int r = u.pm - 65; sb = LP + (r / 33) * LSQ; L = LSQ; i2 = r % 33; }
;         const int sr0 = 254 * i2 - 1;
;         const int tid = (wr * 4 + wc) * 64 + fq * 16 + fr;
;         stage_rstd(lds, ss, tid, (long)sb + sr0, sr0, L);
;         {
;             LAS float* cw = (LAS float*)(lds + EPI_CW);
; #pragma unroll
;             for (int i = 0; i < 2; ++i) {
;                 const int e = tid + 512 * i, bj = e >> 9, k = (e >> 7) & 3, c = e & 127;
;                 cw[e] = k < 3 ? w3[k * 2 * DFF + bj * DFF + u.b0 + c] : b3[bj * DFF + u.b0 + c];
.LBB0_158:
	v_mov_b64_e32 v[2:3], 0x10ee
	v_cmp_lt_i64_e32 vcc, s[0:1], v[2:3]
	s_lshl_b64 s[0:1], s[18:19], 11
	s_add_u32 s40, s16, s0
	s_addc_u32 s41, s17, s1
	s_and_b64 s[0:1], vcc, exec
	s_cselect_b32 s13, s41, s7
	s_cselect_b32 s49, s40, s6
	s_ashr_i32 s37, s36, 31
	s_lshl_b64 s[0:1], s[36:37], 11
	s_add_u32 s42, s51, s0
	s_addc_u32 s43, s52, s1
	s_and_b64 s[0:1], vcc, exec
	s_cselect_b32 s37, s43, s9
	s_cselect_b32 s70, s42, s8
	s_ashr_i32 s39, s38, 31
	s_lshl_b64 s[0:1], s[38:39], 11
	s_add_u32 s44, s51, s0
	s_addc_u32 s45, s52, s1
	s_and_b64 s[0:1], vcc, exec
	s_mov_b32 s88, s72
	s_cselect_b32 s39, s45, s11
	s_cselect_b32 s71, s44, s10
	s_add_u32 s72, s8, 0x100
	s_addc_u32 s73, s9, 0
	s_add_u32 s74, s10, 0x100
	v_mov_b32_e32 v26, 0
	s_addc_u32 s75, s11, 0
	s_mov_b32 s76, -2
	v_mov_b32_e32 v27, v26
	v_mov_b32_e32 v28, v26
	v_mov_b32_e32 v29, v26
	v_mov_b32_e32 v30, v26
	v_mov_b32_e32 v31, v26
	v_mov_b32_e32 v32, v26
	v_mov_b32_e32 v33, v26
	v_mov_b32_e32 v14, v26
	v_mov_b32_e32 v15, v26
	v_mov_b32_e32 v16, v26
	v_mov_b32_e32 v17, v26
	v_mov_b32_e32 v46, v26
	v_mov_b32_e32 v47, v26
	v_mov_b32_e32 v48, v26
	v_mov_b32_e32 v49, v26
	v_mov_b32_e32 v58, v26
	v_mov_b32_e32 v59, v26
	v_mov_b32_e32 v60, v26
	v_mov_b32_e32 v61, v26
	v_mov_b32_e32 v62, v26
	v_mov_b32_e32 v63, v26
	v_mov_b32_e32 v64, v26
	v_mov_b32_e32 v65, v26
	v_mov_b32_e32 v74, v26
	v_mov_b32_e32 v75, v26
	v_mov_b32_e32 v76, v26
	v_mov_b32_e32 v77, v26
	v_mov_b32_e32 v78, v26
	v_mov_b32_e32 v79, v26
	v_mov_b32_e32 v80, v26
	v_mov_b32_e32 v81, v26
	v_mov_b32_e32 v10, v26
	v_mov_b32_e32 v11, v26
	v_mov_b32_e32 v12, v26
	v_mov_b32_e32 v13, v26
	v_mov_b32_e32 v42, v26
	v_mov_b32_e32 v43, v26
	v_mov_b32_e32 v44, v26
	v_mov_b32_e32 v45, v26
	v_mov_b32_e32 v50, v26
	v_mov_b32_e32 v51, v26
	v_mov_b32_e32 v52, v26
	v_mov_b32_e32 v53, v26
	v_mov_b32_e32 v54, v26
	v_mov_b32_e32 v55, v26
	v_mov_b32_e32 v56, v26
	v_mov_b32_e32 v57, v26
	v_mov_b32_e32 v66, v26
	v_mov_b32_e32 v67, v26
	v_mov_b32_e32 v68, v26
	v_mov_b32_e32 v69, v26
	v_mov_b32_e32 v70, v26
	v_mov_b32_e32 v71, v26
	v_mov_b32_e32 v72, v26
	v_mov_b32_e32 v73, v26
	v_mov_b32_e32 v2, v26
	v_mov_b32_e32 v3, v26
	v_mov_b32_e32 v4, v26
	v_mov_b32_e32 v5, v26
	v_mov_b32_e32 v82, v26
	v_mov_b32_e32 v83, v26
	v_mov_b32_e32 v84, v26
	v_mov_b32_e32 v85, v26
	v_mov_b32_e32 v6, v26
	v_mov_b32_e32 v7, v26
	v_mov_b32_e32 v8, v26
	v_mov_b32_e32 v9, v26
	v_mov_b32_e32 v86, v26
	v_mov_b32_e32 v87, v26
	v_mov_b32_e32 v88, v26
	v_mov_b32_e32 v89, v26
	v_mov_b32_e32 v38, v26
	v_mov_b32_e32 v39, v26
	v_mov_b32_e32 v40, v26
	v_mov_b32_e32 v41, v26
	v_mov_b32_e32 v94, v26
	v_mov_b32_e32 v95, v26
	v_mov_b32_e32 v96, v26
	v_mov_b32_e32 v97, v26
	v_mov_b32_e32 v106, v26
	v_mov_b32_e32 v107, v26
	v_mov_b32_e32 v108, v26
	v_mov_b32_e32 v109, v26
	v_mov_b32_e32 v110, v26
	v_mov_b32_e32 v111, v26
	v_mov_b32_e32 v112, v26
	v_mov_b32_e32 v113, v26
	v_mov_b32_e32 v122, v26
	v_mov_b32_e32 v123, v26
	v_mov_b32_e32 v124, v26
	v_mov_b32_e32 v125, v26
	v_mov_b32_e32 v126, v26
	v_mov_b32_e32 v127, v26
	v_mov_b32_e32 v128, v26
	v_mov_b32_e32 v129, v26
	v_mov_b32_e32 v34, v26
	v_mov_b32_e32 v35, v26
	v_mov_b32_e32 v36, v26
	v_mov_b32_e32 v37, v26
	v_mov_b32_e32 v90, v26
	v_mov_b32_e32 v91, v26
	v_mov_b32_e32 v92, v26
	v_mov_b32_e32 v93, v26
	v_mov_b32_e32 v98, v26
	v_mov_b32_e32 v99, v26
	v_mov_b32_e32 v100, v26
	v_mov_b32_e32 v101, v26
	v_mov_b32_e32 v102, v26
	v_mov_b32_e32 v103, v26
	v_mov_b32_e32 v104, v26
	v_mov_b32_e32 v105, v26
	v_mov_b32_e32 v114, v26
	v_mov_b32_e32 v115, v26
	v_mov_b32_e32 v116, v26
	v_mov_b32_e32 v117, v26
	v_mov_b32_e32 v118, v26
	v_mov_b32_e32 v119, v26
	v_mov_b32_e32 v120, v26
	v_mov_b32_e32 v121, v26
	v_mov_b32_e32 v18, v26
	v_mov_b32_e32 v19, v26
	v_mov_b32_e32 v20, v26
	v_mov_b32_e32 v21, v26
	v_mov_b32_e32 v130, v26
	v_mov_b32_e32 v131, v26
	v_mov_b32_e32 v132, v26
	v_mov_b32_e32 v133, v26
	v_lshlrev_b32_e32 v194, 4, v141
	v_add_u32_e32 v194, v194, v140
	v_lshl_add_u32 v194, s63, 6, v194
	v_lshl_add_u32 v194, s53, 8, v194
	v_bfe_u32 v232, v194, 7, 2
	v_mul_u32_u24_e32 v234, 0x1600, v232
	v_cmp_eq_u32_e32 vcc, 3, v232
	v_and_b32_e32 v233, 0x7f, v194
	v_add_u32_e32 v247, 0x200, v194
	v_cndmask_b32_e64 v232, v234, 0, vcc
	v_add3_u32 v246, v233, s12, v232
	v_mov_b32_e32 v232, s60
	v_mov_b32_e32 v233, s62
	v_ashrrev_i32_e32 v235, 9, v194
	v_cndmask_b32_e32 v233, v232, v233, vcc
	v_mov_b32_e32 v232, s59
	v_mov_b32_e32 v234, s61
	s_movk_i32 s32, 0xb00
	v_ashrrev_i32_e32 v247, 9, v247
	v_cndmask_b32_e32 v232, v232, v234, vcc
	v_mad_i32_i24 v234, v235, s32, v246
	v_mad_i32_i24 v246, v247, s32, v246
	v_ashrrev_i32_e32 v235, 31, v234
	v_ashrrev_i32_e32 v247, 31, v246
	v_lshl_add_u64 v[234:235], v[234:235], 2, v[232:233]
	v_lshl_add_u64 v[232:233], v[246:247], 2, v[232:233]
	global_load_dword v248, v[234:235], off
	s_nop 0
	global_load_dword v249, v[232:233], off
	s_cmp_lg_u32 s53, 0
	s_cbranch_scc1 .Lmy_up_pf_done
	s_add_i32 s98, s48, 0xffffffbf
	s_mul_hi_u32 s99, s98, 0x3e0f83e1
	s_lshr_b32 s99, s99, 3
	s_mul_i32 s32, s99, 33
	s_sub_i32 s98, s98, s32
	s_lshl_b32 s99, s99, 13
	s_add_i32 s99, s99, 0x4000
	s_movk_i32 s32, 0x2000
	s_cmpk_lt_i32 s48, 0x41
	s_cselect_b32 s98, s48, s98
	s_cselect_b32 s99, 0, s99
	s_cselect_b32 s32, 0x4000, s32
	s_mul_i32 s98, s98, 0xfe
	s_add_i32 s98, s98, -1
	v_add_u32_e32 v195, s98, v194
	v_cmp_gt_u32_e32 vcc, s32, v195
	v_add_u32_e32 v195, s99, v195
	s_nop 1
	v_cndmask_b32_e32 v195, 0, v195, vcc
	v_lshlrev_b32_e32 v196, 6, v195
	v_mov_b32_e32 v197, 0
	v_readlane_b32 s98, v254, 22
	v_readlane_b32 s99, v254, 23
	s_nop 3
	s_load_dwordx2 s[98:99], s[98:99], 0x120
	s_waitcnt lgkmcnt(0)
	v_lshl_add_u64 v[196:197], s[98:99], 0, v[196:197]
	global_load_dwordx4 v[206:209], v[196:197], off offset:48
	global_load_dwordx4 v[210:213], v[196:197], off offset:32
	global_load_dwordx4 v[222:225], v[196:197], off offset:16
	global_load_dwordx4 v[226:229], v[196:197], off
; #define G_STAGE(bufoff, gbase, voff) do { const char* _gb = (const char*)(gbase); asm volatile("" : "+s"(_gb)); _Pragma("unroll") for (int _i = 0; _i < 2; ++_i) \
;         __builtin_amdgcn_global_load_lds((const unsigned*)(_gb + (voff)[_i]), (LAS unsigned*)(lds + (bufoff) + ldsw + _i * 8192), 16, 0, 0); } while (0)
; #define G_LDA(dst, b, h) do { _Pragma("unroll") for (int m = 0; m < 4; ++m) _Pragma("unroll") for (int k = 0; k < 2; ++k) dst[m][k] = *(const LAS bf16x8*)(lds + G_SA(b, h) + aoff + m * 2048 + k * 1024); } while (0)
; #define G_LDB(dst, b, h) do { _Pragma("unroll") for (int n = 0; n < 2; ++n) _Pragma("unroll") for (int k = 0; k < 2; ++k) dst[n][k] = *(const LAS bf16x8*)(lds + G_SB(b, h) + boff + n * 2048 + k * 1024); } while (0)
; #define G_WAIT_L(n) asm volatile("s_waitcnt lgkmcnt(" #n ")" ::: "memory")
; #define G_BAR __builtin_amdgcn_s_barrier()
; #define G_SCHED __builtin_amdgcn_sched_barrier(0)
; template <class Epi>
; __device__ __forceinline__ void gemm_phase(LAS unsigned char* lds, const bf16_t* Ag, const bf16_t* Btg, const int K, const Sched& S, const Epi& E, int wv) {
;     ...
;         const bool has_next = S.next(ui + 1, nxt);
;         const char* nA = has_next ? (const char*)Ag + nxt.arow * (long)rowb : cA;
;         const char* nB0 = has_next ? (const char*)Btg + (size_t)nxt.b0 * rowb : cB0;
;         const char* nB1 = has_next ? (const char*)Btg + (size_t)nxt.b1 * rowb : cB1;
;         for (int t = 0; t < nt; t += 2) {
;             const bool last = (t == nt - 2);
;             const char* a1 = cA + (size_t)(t + 1) * kstep;
;             const char* a2 = last ? nA : cA + (size_t)(t + 2) * kstep;
;             const char* b20 = last ? nB0 : cB0 + (size_t)(t + 2) * kstep;
;             const char* b21 = last ? nB1 : cB1 + (size_t)(t + 2) * kstep;
;             const char* a3 = a2 + kstep; const char* b30 = b20 + kstep; const char* b31 = b21 + kstep;
;             G_LDB(B0, 0, 0); G_SCHED; G_LDA(At, 0, 0); G_STAGE(G_SA(1, 1), a1 + hstep, voffA);
;             G_WAIT_L(8); G_BAR; G_WAIT_L(0); G_MMA(0, 0, At, B0); G_BAR; G_SCHED;
;             G_LDB(B1, 0, 1); G_STAGE(G_SB(0, 0), b20, voffB);
;             G_BAR; G_WAIT_L(0); G_MMA(0, 1, At, B1); G_BAR;
;             G_LDA(At, 0, 1); G_STAGE(G_SA(0, 0), a2, voffA);
;             G_BAR; G_WAIT_L(0); G_MMA(1, 0, At, B0); G_BAR; G_SCHED;
.Lmy_up_pf_done:
.LBB0_159:
	s_add_u32 s0, s6, 0x100
	s_addc_u32 s1, s7, 0
	s_cmp_eq_u32 s76, 12
	s_cselect_b32 s78, s70, s72
	s_cselect_b32 s79, s37, s73
	s_cselect_b32 s3, s39, s75
	s_cselect_b32 s2, s71, s74
	s_cselect_b32 s46, s49, s0
	s_cselect_b32 s47, s13, s1
	s_add_u32 s10, s78, 0x80
	s_addc_u32 s11, s79, 0
	s_add_i32 s77, 0, 0x10000
	v_add_u32_e32 v152, s77, v142
	ds_read_b128 v[22:25], v152
	ds_read_b128 v[144:147], v152 offset:1024
	ds_read_b128 v[148:151], v152 offset:2048
	ds_read_b128 v[152:155], v152 offset:3072
	s_add_u32 s8, s46, 0x80
	s_addc_u32 s9, s47, 0
	s_add_u32 s6, s6, 0x40080
	s_addc_u32 s7, s7, 0
	ds_read_b128 v[156:159], v143
	ds_read_b128 v[160:163], v143 offset:1024
	ds_read_b128 v[164:167], v143 offset:2048
	ds_read_b128 v[168:171], v143 offset:3072
	ds_read_b128 v[172:175], v143 offset:4096
	ds_read_b128 v[176:179], v143 offset:5120
	ds_read_b128 v[180:183], v143 offset:6144
	ds_read_b128 v[184:187], v143 offset:7168
	s_add_i32 m0, s55, 0xc000
	v_lshl_add_u64 v[188:189], s[6:7], 0, v[134:135]
	global_load_lds_dwordx4 v[188:189], off
	v_lshl_add_u64 v[188:189], s[6:7], 0, v[136:137]
	s_add_i32 m0, s55, 0xe000
	s_nop 0
	global_load_lds_dwordx4 v[188:189], off
	s_waitcnt lgkmcnt(8)
	s_barrier
	s_waitcnt lgkmcnt(0)
	s_setprio 1
	s_waitcnt lgkmcnt(0)
	v_mfma_f32_16x16x32_bf16 v[130:133], v[22:25], v[156:159], v[130:133]
	v_mfma_f32_16x16x32_bf16 v[18:21], v[148:151], v[156:159], v[18:21]
	v_mfma_f32_16x16x32_bf16 v[118:121], v[22:25], v[164:167], v[118:121]
	v_mfma_f32_16x16x32_bf16 v[114:117], v[148:151], v[164:167], v[114:117]
	v_mfma_f32_16x16x32_bf16 v[102:105], v[22:25], v[172:175], v[102:105]
	v_mfma_f32_16x16x32_bf16 v[98:101], v[148:151], v[172:175], v[98:101]
	v_mfma_f32_16x16x32_bf16 v[90:93], v[22:25], v[180:183], v[90:93]
	v_mfma_f32_16x16x32_bf16 v[34:37], v[148:151], v[180:183], v[34:37]
	v_mfma_f32_16x16x32_bf16 v[130:133], v[144:147], v[160:163], v[130:133]
	v_mfma_f32_16x16x32_bf16 v[18:21], v[152:155], v[160:163], v[18:21]
	v_mfma_f32_16x16x32_bf16 v[118:121], v[144:147], v[168:171], v[118:121]
	v_mfma_f32_16x16x32_bf16 v[114:117], v[152:155], v[168:171], v[114:117]
	v_mfma_f32_16x16x32_bf16 v[102:105], v[144:147], v[176:179], v[102:105]
	v_mfma_f32_16x16x32_bf16 v[98:101], v[152:155], v[176:179], v[98:101]
	v_mfma_f32_16x16x32_bf16 v[90:93], v[144:147], v[184:187], v[90:93]
	v_mfma_f32_16x16x32_bf16 v[34:37], v[152:155], v[184:187], v[34:37]
	s_setprio 0
	s_barrier
	s_add_i32 s80, 0, 0x14000
	v_add_u32_e32 v192, s80, v142
	s_add_i32 s6, s77, s54
	ds_read_b128 v[188:191], v192
	ds_read_b128 v[200:203], v192 offset:1024
	ds_read_b128 v[214:217], v192 offset:2048
	ds_read_b128 v[218:221], v192 offset:3072
	s_mov_b32 m0, s6
	v_lshl_add_u64 v[192:193], s[78:79], 0, v[0:1]
	global_load_lds_dwordx4 v[192:193], off
	v_lshl_add_u64 v[192:193], s[78:79], 0, v[138:139]
	s_add_i32 m0, s6, 0x2000
	s_nop 0
	global_load_lds_dwordx4 v[192:193], off
	s_barrier
	s_waitcnt lgkmcnt(0)
	s_setprio 1
	s_waitcnt lgkmcnt(0)
	v_mfma_f32_16x16x32_bf16 v[126:129], v[188:191], v[156:159], v[126:129]
	v_mfma_f32_16x16x32_bf16 v[122:125], v[214:217], v[156:159], v[122:125]
	v_mfma_f32_16x16x32_bf16 v[110:113], v[188:191], v[164:167], v[110:113]
	v_mfma_f32_16x16x32_bf16 v[106:109], v[214:217], v[164:167], v[106:109]
	v_mfma_f32_16x16x32_bf16 v[94:97], v[188:191], v[172:175], v[94:97]
	v_mfma_f32_16x16x32_bf16 v[38:41], v[214:217], v[172:175], v[38:41]
	v_mfma_f32_16x16x32_bf16 v[86:89], v[188:191], v[180:183], v[86:89]
	v_mfma_f32_16x16x32_bf16 v[6:9], v[214:217], v[180:183], v[6:9]
	v_mfma_f32_16x16x32_bf16 v[126:129], v[200:203], v[160:163], v[126:129]
	v_mfma_f32_16x16x32_bf16 v[122:125], v[218:221], v[160:163], v[122:125]
	v_mfma_f32_16x16x32_bf16 v[110:113], v[200:203], v[168:171], v[110:113]
	v_mfma_f32_16x16x32_bf16 v[106:109], v[218:221], v[168:171], v[106:109]
	v_mfma_f32_16x16x32_bf16 v[94:97], v[200:203], v[176:179], v[94:97]
	v_mfma_f32_16x16x32_bf16 v[38:41], v[218:221], v[176:179], v[38:41]
	v_mfma_f32_16x16x32_bf16 v[86:89], v[200:203], v[184:187], v[86:89]
	v_mfma_f32_16x16x32_bf16 v[6:9], v[218:221], v[184:187], v[6:9]
	s_setprio 0
	s_mov_b64 s[6:7], s[46:47]
	s_mov_b32 m0, s55
	s_barrier
	ds_read_b128 v[156:159], v143 offset:16384
	ds_read_b128 v[160:163], v143 offset:17408
	ds_read_b128 v[164:167], v143 offset:18432
	ds_read_b128 v[168:171], v143 offset:19456
	ds_read_b128 v[172:175], v143 offset:20480
	ds_read_b128 v[176:179], v143 offset:21504
	ds_read_b128 v[180:183], v143 offset:22528
	ds_read_b128 v[184:187], v143 offset:23552
	s_nop 0
	v_lshl_add_u64 v[192:193], s[6:7], 0, v[134:135]
	global_load_lds_dwordx4 v[192:193], off
	v_lshl_add_u64 v[192:193], s[6:7], 0, v[136:137]
	s_mov_b32 m0, s56
	s_nop 0
	global_load_lds_dwordx4 v[192:193], off
	s_barrier
	s_waitcnt lgkmcnt(0)
	s_setprio 1
	s_waitcnt lgkmcnt(0)
	v_mfma_f32_16x16x32_bf16 v[82:85], v[22:25], v[156:159], v[82:85]
	v_mfma_f32_16x16x32_bf16 v[2:5], v[148:151], v[156:159], v[2:5]
	v_mfma_f32_16x16x32_bf16 v[70:73], v[22:25], v[164:167], v[70:73]
	v_mfma_f32_16x16x32_bf16 v[66:69], v[148:151], v[164:167], v[66:69]
	v_mfma_f32_16x16x32_bf16 v[54:57], v[22:25], v[172:175], v[54:57]
	v_mfma_f32_16x16x32_bf16 v[50:53], v[148:151], v[172:175], v[50:53]
	v_mfma_f32_16x16x32_bf16 v[10:13], v[148:151], v[180:183], v[10:13]
	v_mfma_f32_16x16x32_bf16 v[82:85], v[144:147], v[160:163], v[82:85]
	v_mfma_f32_16x16x32_bf16 v[2:5], v[152:155], v[160:163], v[2:5]
	v_mfma_f32_16x16x32_bf16 v[70:73], v[144:147], v[168:171], v[70:73]
	v_mfma_f32_16x16x32_bf16 v[66:69], v[152:155], v[168:171], v[66:69]
	v_mfma_f32_16x16x32_bf16 v[54:57], v[144:147], v[176:179], v[54:57]
	v_mfma_f32_16x16x32_bf16 v[50:53], v[152:155], v[176:179], v[50:53]
	v_mfma_f32_16x16x32_bf16 v[22:25], v[22:25], v[180:183], v[42:45]
	v_mfma_f32_16x16x32_bf16 v[10:13], v[152:155], v[184:187], v[10:13]
	v_mfma_f32_16x16x32_bf16 v[22:25], v[144:147], v[184:187], v[22:25]
	s_setprio 0
	s_barrier
; #define G_STAGE(bufoff, gbase, voff) do { const char* _gb = (const char*)(gbase); asm volatile("" : "+s"(_gb)); _Pragma("unroll") for (int _i = 0; _i < 2; ++_i) \
;         __builtin_amdgcn_global_load_lds((const unsigned*)(_gb + (voff)[_i]), (LAS unsigned*)(lds + (bufoff) + ldsw + _i * 8192), 16, 0, 0); } while (0)
; #define G_LDA(dst, b, h) do { _Pragma("unroll") for (int m = 0; m < 4; ++m) _Pragma("unroll") for (int k = 0; k < 2; ++k) dst[m][k] = *(const LAS bf16x8*)(lds + G_SA(b, h) + aoff + m * 2048 + k * 1024); } while (0)
; #define G_LDB(dst, b, h) do { _Pragma("unroll") for (int n = 0; n < 2; ++n) _Pragma("unroll") for (int k = 0; k < 2; ++k) dst[n][k] = *(const LAS bf16x8*)(lds + G_SB(b, h) + boff + n * 2048 + k * 1024); } while (0)
; #define G_MMA(ai, bj, At, Bt) do { __builtin_amdgcn_s_setprio(1); _Pragma("unroll") for (int m = 0; m < 4; ++m) _Pragma("unroll") for (int n = 0; n < 2; ++n) _Pragma("unroll") for (int k = 0; k < 2; ++k) \
;         acc[ai][bj][m][n] = __builtin_amdgcn_mfma_f32_16x16x32_bf16(Bt[n][k], At[m][k], acc[ai][bj][m][n], 0, 0, 0); __builtin_amdgcn_s_setprio(0); } while (0)
; #define G_WAIT_V(n) asm volatile("s_waitcnt vmcnt(" #n ")" ::: "memory")
; #define G_WAIT_L(n) asm volatile("s_waitcnt lgkmcnt(" #n ")" ::: "memory")
; #define G_BAR __builtin_amdgcn_s_barrier()
; #define G_SCHED __builtin_amdgcn_sched_barrier(0)
; template <class Epi>
; __device__ __forceinline__ void gemm_phase(LAS unsigned char* lds, const bf16_t* Ag, const bf16_t* Btg, const int K, const Sched& S, const Epi& E, int wv) {
;     ...
;             G_STAGE(G_SB(0, 1), b21, voffB);
;             G_WAIT_V(6); G_BAR; G_MMA(1, 1, At, B1); G_BAR;
;             G_LDB(B0, 1, 0); G_SCHED; G_LDA(At, 1, 0); G_STAGE(G_SA(0, 1), a2 + hstep, voffA);
;             G_WAIT_L(8); G_BAR; G_WAIT_L(0); G_MMA(0, 0, At, B0); G_BAR; G_SCHED;
;             G_LDB(B1, 1, 1); G_STAGE(G_SB(1, 0), b30, voffB);
;             G_BAR; G_WAIT_L(0); G_MMA(0, 1, At, B1); G_BAR;
;             G_LDA(At, 1, 1); G_STAGE(G_SA(1, 0), a3, voffA);
;             G_BAR; G_WAIT_L(0); G_MMA(1, 0, At, B0); G_BAR; G_SCHED;
	s_mov_b64 s[6:7], s[2:3]
	s_add_i32 s77, s80, s54
	s_mov_b32 m0, s77
	v_lshl_add_u64 v[42:43], s[6:7], 0, v[0:1]
	global_load_lds_dwordx4 v[42:43], off
	v_lshl_add_u64 v[42:43], s[6:7], 0, v[138:139]
	s_add_i32 m0, s77, 0x2000
	s_nop 0
	global_load_lds_dwordx4 v[42:43], off
	s_waitcnt vmcnt(6)
	s_barrier
	s_setprio 1
	v_mfma_f32_16x16x32_bf16 v[42:45], v[188:191], v[156:159], v[78:81]
	v_mfma_f32_16x16x32_bf16 v[78:81], v[200:203], v[160:163], v[42:45]
	v_mfma_f32_16x16x32_bf16 v[42:45], v[214:217], v[156:159], v[74:77]
	v_mfma_f32_16x16x32_bf16 v[74:77], v[218:221], v[160:163], v[42:45]
	v_mfma_f32_16x16x32_bf16 v[42:45], v[188:191], v[164:167], v[62:65]
	v_mfma_f32_16x16x32_bf16 v[62:65], v[200:203], v[168:171], v[42:45]
	v_mfma_f32_16x16x32_bf16 v[42:45], v[214:217], v[164:167], v[58:61]
	v_mfma_f32_16x16x32_bf16 v[58:61], v[218:221], v[168:171], v[42:45]
	v_mfma_f32_16x16x32_bf16 v[42:45], v[188:191], v[172:175], v[46:49]
	v_mfma_f32_16x16x32_bf16 v[14:17], v[214:217], v[172:175], v[14:17]
	v_mfma_f32_16x16x32_bf16 v[30:33], v[188:191], v[180:183], v[30:33]
	v_mfma_f32_16x16x32_bf16 v[26:29], v[214:217], v[180:183], v[26:29]
	v_mfma_f32_16x16x32_bf16 v[46:49], v[200:203], v[176:179], v[42:45]
	v_mfma_f32_16x16x32_bf16 v[14:17], v[218:221], v[176:179], v[14:17]
	v_mfma_f32_16x16x32_bf16 v[30:33], v[200:203], v[184:187], v[30:33]
	v_mfma_f32_16x16x32_bf16 v[26:29], v[218:221], v[184:187], v[26:29]
	s_setprio 0
	s_add_i32 s77, 0, 0x18000
	v_add_u32_e32 v152, s77, v142
	s_barrier
	ds_read_b128 v[42:45], v152
	ds_read_b128 v[144:147], v152 offset:1024
	ds_read_b128 v[148:151], v152 offset:2048
	ds_read_b128 v[152:155], v152 offset:3072
	s_add_u32 s6, s46, 0x40000
	s_addc_u32 s7, s47, 0
	s_mov_b32 m0, s57
	ds_read_b128 v[156:159], v143 offset:32768
	ds_read_b128 v[160:163], v143 offset:33792
	ds_read_b128 v[164:167], v143 offset:34816
	ds_read_b128 v[168:171], v143 offset:35840
	ds_read_b128 v[172:175], v143 offset:36864
	ds_read_b128 v[176:179], v143 offset:37888
	ds_read_b128 v[180:183], v143 offset:38912
	ds_read_b128 v[184:187], v143 offset:39936
	s_nop 0
	v_lshl_add_u64 v[188:189], s[6:7], 0, v[134:135]
	global_load_lds_dwordx4 v[188:189], off
	v_lshl_add_u64 v[188:189], s[6:7], 0, v[136:137]
	s_mov_b32 m0, s58
	s_nop 0
	global_load_lds_dwordx4 v[188:189], off
	s_waitcnt lgkmcnt(8)
	s_barrier
	s_waitcnt lgkmcnt(0)
	s_setprio 1
	s_waitcnt lgkmcnt(0)
	v_mfma_f32_16x16x32_bf16 v[130:133], v[42:45], v[156:159], v[130:133]
	v_mfma_f32_16x16x32_bf16 v[18:21], v[148:151], v[156:159], v[18:21]
	v_mfma_f32_16x16x32_bf16 v[118:121], v[42:45], v[164:167], v[118:121]
	v_mfma_f32_16x16x32_bf16 v[114:117], v[148:151], v[164:167], v[114:117]
	v_mfma_f32_16x16x32_bf16 v[102:105], v[42:45], v[172:175], v[102:105]
	v_mfma_f32_16x16x32_bf16 v[98:101], v[148:151], v[172:175], v[98:101]
	v_mfma_f32_16x16x32_bf16 v[90:93], v[42:45], v[180:183], v[90:93]
	v_mfma_f32_16x16x32_bf16 v[34:37], v[148:151], v[180:183], v[34:37]
	v_mfma_f32_16x16x32_bf16 v[130:133], v[144:147], v[160:163], v[130:133]
	v_mfma_f32_16x16x32_bf16 v[18:21], v[152:155], v[160:163], v[18:21]
	v_mfma_f32_16x16x32_bf16 v[118:121], v[144:147], v[168:171], v[118:121]
	v_mfma_f32_16x16x32_bf16 v[114:117], v[152:155], v[168:171], v[114:117]
	v_mfma_f32_16x16x32_bf16 v[102:105], v[144:147], v[176:179], v[102:105]
	v_mfma_f32_16x16x32_bf16 v[98:101], v[152:155], v[176:179], v[98:101]
	v_mfma_f32_16x16x32_bf16 v[90:93], v[144:147], v[184:187], v[90:93]
	v_mfma_f32_16x16x32_bf16 v[34:37], v[152:155], v[184:187], v[34:37]
	s_setprio 0
	s_barrier
	s_add_i32 s6, 0, 0x1c000
	v_add_u32_e32 v192, s6, v142
	s_add_i32 s7, s77, s54
	ds_read_b128 v[188:191], v192
	ds_read_b128 v[200:203], v192 offset:1024
	ds_read_b128 v[214:217], v192 offset:2048
	ds_read_b128 v[218:221], v192 offset:3072
	s_mov_b32 m0, s7
	v_lshl_add_u64 v[192:193], s[10:11], 0, v[0:1]
	global_load_lds_dwordx4 v[192:193], off
	v_lshl_add_u64 v[192:193], s[10:11], 0, v[138:139]
	s_add_i32 m0, s7, 0x2000
	s_nop 0
	global_load_lds_dwordx4 v[192:193], off
	s_barrier
; #define G_STAGE(bufoff, gbase, voff) do { const char* _gb = (const char*)(gbase); asm volatile("" : "+s"(_gb)); _Pragma("unroll") for (int _i = 0; _i < 2; ++_i) \
;         __builtin_amdgcn_global_load_lds((const unsigned*)(_gb + (voff)[_i]), (LAS unsigned*)(lds + (bufoff) + ldsw + _i * 8192), 16, 0, 0); } while (0)
; #define G_MMA(ai, bj, At, Bt) do { __builtin_amdgcn_s_setprio(1); _Pragma("unroll") for (int m = 0; m < 4; ++m) _Pragma("unroll") for (int n = 0; n < 2; ++n) _Pragma("unroll") for (int k = 0; k < 2; ++k) \
;         acc[ai][bj][m][n] = __builtin_amdgcn_mfma_f32_16x16x32_bf16(Bt[n][k], At[m][k], acc[ai][bj][m][n], 0, 0, 0); __builtin_amdgcn_s_setprio(0); } while (0)
; #define G_WAIT_V(n) asm volatile("s_waitcnt vmcnt(" #n ")" ::: "memory")
; #define G_WAIT_L(n) asm volatile("s_waitcnt lgkmcnt(" #n ")" ::: "memory")
; #define G_BAR __builtin_amdgcn_s_barrier()
; #define G_SCHED __builtin_amdgcn_sched_barrier(0)
; template <class Epi>
; __device__ __forceinline__ void gemm_phase(LAS unsigned char* lds, const bf16_t* Ag, const bf16_t* Btg, const int K, const Sched& S, const Epi& E, int wv) {
;     ...
;             G_BAR; G_WAIT_L(0); G_MMA(1, 0, At, B0); G_BAR; G_SCHED;
;             G_STAGE(G_SB(1, 1), b31, voffB);
;             G_WAIT_V(6); G_BAR; G_MMA(1, 1, At, B1); G_BAR;
;     __device__ __forceinline__ void operator()(f32x4 (&acc)[2][2][4][2], const Unit& u, int wr, int wc, int fr, int fq, LAS unsigned char* lds) const {
;     ...
;         int sb, L, i2; if (u.pm < 65) { sb = 0; L = LP; i2 = u.pm; } else { const int r = u.pm - 65; sb = LP + (r / 33) * LSQ; L = LSQ; i2 = r % 33; }
	s_waitcnt lgkmcnt(0)
	s_setprio 1
	s_waitcnt lgkmcnt(0)
	v_mfma_f32_16x16x32_bf16 v[126:129], v[188:191], v[156:159], v[126:129]
	v_mfma_f32_16x16x32_bf16 v[122:125], v[214:217], v[156:159], v[122:125]
	v_mfma_f32_16x16x32_bf16 v[110:113], v[188:191], v[164:167], v[110:113]
	v_mfma_f32_16x16x32_bf16 v[106:109], v[214:217], v[164:167], v[106:109]
	v_mfma_f32_16x16x32_bf16 v[94:97], v[188:191], v[172:175], v[94:97]
	v_mfma_f32_16x16x32_bf16 v[38:41], v[214:217], v[172:175], v[38:41]
	v_mfma_f32_16x16x32_bf16 v[86:89], v[188:191], v[180:183], v[86:89]
	v_mfma_f32_16x16x32_bf16 v[6:9], v[214:217], v[180:183], v[6:9]
	v_mfma_f32_16x16x32_bf16 v[126:129], v[200:203], v[160:163], v[126:129]
	v_mfma_f32_16x16x32_bf16 v[122:125], v[218:221], v[160:163], v[122:125]
	v_mfma_f32_16x16x32_bf16 v[110:113], v[200:203], v[168:171], v[110:113]
	v_mfma_f32_16x16x32_bf16 v[106:109], v[218:221], v[168:171], v[106:109]
	v_mfma_f32_16x16x32_bf16 v[94:97], v[200:203], v[176:179], v[94:97]
	v_mfma_f32_16x16x32_bf16 v[38:41], v[218:221], v[176:179], v[38:41]
	v_mfma_f32_16x16x32_bf16 v[86:89], v[200:203], v[184:187], v[86:89]
	v_mfma_f32_16x16x32_bf16 v[6:9], v[218:221], v[184:187], v[6:9]
	s_setprio 0
	s_mov_b32 m0, s64
	s_barrier
	ds_read_b128 v[156:159], v143 offset:49152
	ds_read_b128 v[160:163], v143 offset:50176
	ds_read_b128 v[164:167], v143 offset:51200
	ds_read_b128 v[168:171], v143 offset:52224
	ds_read_b128 v[172:175], v143 offset:53248
	ds_read_b128 v[176:179], v143 offset:54272
	ds_read_b128 v[180:183], v143 offset:55296
	ds_read_b128 v[184:187], v143 offset:56320
	s_nop 0
	v_lshl_add_u64 v[192:193], s[8:9], 0, v[134:135]
	global_load_lds_dwordx4 v[192:193], off
	v_lshl_add_u64 v[192:193], s[8:9], 0, v[136:137]
	s_mov_b32 m0, s65
	s_nop 0
	global_load_lds_dwordx4 v[192:193], off
	s_barrier
	s_waitcnt lgkmcnt(0)
	s_setprio 1
	s_waitcnt lgkmcnt(0)
	v_mfma_f32_16x16x32_bf16 v[82:85], v[42:45], v[156:159], v[82:85]
	s_add_u32 s2, s2, 0x80
	s_addc_u32 s3, s3, 0
	v_mfma_f32_16x16x32_bf16 v[2:5], v[148:151], v[156:159], v[2:5]
	v_mfma_f32_16x16x32_bf16 v[70:73], v[42:45], v[164:167], v[70:73]
	v_mfma_f32_16x16x32_bf16 v[66:69], v[148:151], v[164:167], v[66:69]
	v_mfma_f32_16x16x32_bf16 v[54:57], v[42:45], v[172:175], v[54:57]
	v_mfma_f32_16x16x32_bf16 v[50:53], v[148:151], v[172:175], v[50:53]
	v_mfma_f32_16x16x32_bf16 v[22:25], v[42:45], v[180:183], v[22:25]
	v_mfma_f32_16x16x32_bf16 v[10:13], v[148:151], v[180:183], v[10:13]
	v_mfma_f32_16x16x32_bf16 v[82:85], v[144:147], v[160:163], v[82:85]
	v_mfma_f32_16x16x32_bf16 v[2:5], v[152:155], v[160:163], v[2:5]
	v_mfma_f32_16x16x32_bf16 v[70:73], v[144:147], v[168:171], v[70:73]
	v_mfma_f32_16x16x32_bf16 v[66:69], v[152:155], v[168:171], v[66:69]
	v_mfma_f32_16x16x32_bf16 v[54:57], v[144:147], v[176:179], v[54:57]
	v_mfma_f32_16x16x32_bf16 v[50:53], v[152:155], v[176:179], v[50:53]
	v_mfma_f32_16x16x32_bf16 v[42:45], v[144:147], v[184:187], v[22:25]
	v_mfma_f32_16x16x32_bf16 v[10:13], v[152:155], v[184:187], v[10:13]
	s_setprio 0
	s_barrier
	s_add_i32 s6, s6, s54
	s_mov_b32 m0, s6
	v_lshl_add_u64 v[22:23], s[2:3], 0, v[0:1]
	global_load_lds_dwordx4 v[22:23], off
	v_lshl_add_u64 v[22:23], s[2:3], 0, v[138:139]
	s_add_i32 m0, s6, 0x2000
	s_nop 0
	global_load_lds_dwordx4 v[22:23], off
	s_waitcnt vmcnt(6)
	s_barrier
	s_setprio 1
	v_mfma_f32_16x16x32_bf16 v[22:25], v[188:191], v[156:159], v[78:81]
	v_mfma_f32_16x16x32_bf16 v[78:81], v[200:203], v[160:163], v[22:25]
	v_mfma_f32_16x16x32_bf16 v[22:25], v[214:217], v[156:159], v[74:77]
	v_mfma_f32_16x16x32_bf16 v[74:77], v[218:221], v[160:163], v[22:25]
	v_mfma_f32_16x16x32_bf16 v[22:25], v[188:191], v[164:167], v[62:65]
	v_mfma_f32_16x16x32_bf16 v[62:65], v[200:203], v[168:171], v[22:25]
	v_mfma_f32_16x16x32_bf16 v[22:25], v[214:217], v[164:167], v[58:61]
	v_mfma_f32_16x16x32_bf16 v[58:61], v[218:221], v[168:171], v[22:25]
	v_mfma_f32_16x16x32_bf16 v[22:25], v[188:191], v[172:175], v[46:49]
	v_mfma_f32_16x16x32_bf16 v[46:49], v[200:203], v[176:179], v[22:25]
	v_mfma_f32_16x16x32_bf16 v[22:25], v[188:191], v[180:183], v[30:33]
	v_mfma_f32_16x16x32_bf16 v[14:17], v[214:217], v[172:175], v[14:17]
	v_mfma_f32_16x16x32_bf16 v[30:33], v[200:203], v[184:187], v[22:25]
	v_mfma_f32_16x16x32_bf16 v[22:25], v[214:217], v[180:183], v[26:29]
	v_mfma_f32_16x16x32_bf16 v[14:17], v[218:221], v[176:179], v[14:17]
	v_mfma_f32_16x16x32_bf16 v[26:29], v[218:221], v[184:187], v[22:25]
	s_setprio 0
	s_add_i32 s76, s76, 2
	s_add_u32 s72, s72, 0x100
	s_addc_u32 s73, s73, 0
	s_add_u32 s74, s74, 0x100
	s_addc_u32 s75, s75, 0
	s_cmp_gt_u32 s76, 13
	s_mov_b64 s[6:7], s[0:1]
	s_barrier
	s_cbranch_scc0 .LBB0_159
	v_mov_b32_e32 v145, v141
	s_mov_b32 s6, s63
	v_mov_b32_e32 v144, v140
	s_mov_b32 s13, s53
	s_cmpk_lt_i32 s48, 0x41
	s_cbranch_scc1 .LBB0_162
	s_addk_i32 s48, 0xffbf
	s_mul_hi_u32 s0, s48, 0x3e0f83e1
	s_lshr_b32 s0, s0, 3
	s_lshl_b32 s1, s0, 13
	s_mul_i32 s0, s0, 33
	s_add_i32 s46, s1, 0x4000
	s_sub_i32 s48, s48, s0
	s_movk_i32 s37, 0x2000
	s_branch .LBB0_163

; #define LAS __attribute__((address_space(3)))
; __device__ __forceinline__ void stage_rstd(LAS unsigned char* lds, const float* ss, int tid, long grow0, int sr0, int L) {
;     if (tid < 256) {
;         const int sr = sr0 + tid; const bool valid = sr >= 0 && sr < L;
;         const f32x4* q = (const f32x4*)(ss + (size_t)(valid ? grow0 + tid : 0) * 16);
;         const f32x4 a = q[0], b = q[1], c = q[2], d = q[3];
;         const float sm_ = ((a.x + a.y) + (a.z + a.w)) + ((b.x + b.y) + (b.z + b.w)) + ((c.x + c.y) + (c.z + c.w)) + ((d.x + d.y) + (d.z + d.w));
;         ((LAS float*)(lds + EPI_RS))[tid] = valid ? rsqrtf(sm_ * (1.0f / 1024.0f) + EPS) : 0.f;
.LBB0_163:
	v_lshlrev_b32_e64 v24, 8, s13
	v_lshlrev_b32_e32 v22, 4, v145
	v_lshl_add_u32 v23, s6, 6, v144
	s_mul_i32 s39, s48, 0xfe
	v_add3_u32 v25, v23, v24, v22
	s_movk_i32 s0, 0x100
	s_mov_b32 s72, s88
	s_add_i32 s39, s39, -1
	v_cmp_gt_i32_e32 vcc, s0, v25
	s_and_saveexec_b64 s[0:1], vcc
	s_cbranch_execz .LBB0_167
	v_add_u32_e32 v22, s39, v25
	v_cmp_gt_u32_e32 vcc, s37, v22
	v_mov_b32_e32 v23, 0
	s_and_saveexec_b64 s[2:3], vcc
	s_cbranch_execz .LBB0_166
	s_mov_b32 s47, s72
	v_mov_b32_e32 v146, v206
	v_mov_b32_e32 v147, v207
	v_mov_b32_e32 v148, v208
	v_mov_b32_e32 v149, v209
	v_mov_b32_e32 v150, v210
	v_mov_b32_e32 v151, v211
	v_mov_b32_e32 v152, v212
	v_mov_b32_e32 v153, v213
	v_mov_b32_e32 v154, v222
	v_mov_b32_e32 v155, v223
	v_mov_b32_e32 v156, v224
	v_mov_b32_e32 v157, v225
	v_mov_b32_e32 v158, v226
	v_mov_b32_e32 v159, v227
	v_mov_b32_e32 v160, v228
	v_mov_b32_e32 v161, v229
	s_mov_b32 s7, 0x800000
	v_add_f32_e32 v150, v150, v151
	v_add_f32_e32 v152, v152, v153
	v_mov_b32_e32 v22, v159
	v_mov_b32_e32 v23, v160
	v_mov_b32_e32 v159, v161
	v_pk_add_f32 v[22:23], v[22:23], v[158:159]
	v_mov_b32_e32 v158, v155
	v_mov_b32_e32 v159, v156
	v_mov_b32_e32 v155, v157
	v_pk_add_f32 v[154:155], v[158:159], v[154:155]
	v_pk_add_f32 v[22:23], v[22:23], v[22:23] op_sel:[0,1] op_sel_hi:[1,0]
	v_pk_add_f32 v[154:155], v[154:155], v[154:155] op_sel:[0,1] op_sel_hi:[1,0]
	v_mov_b32_e32 v23, v146
	v_mov_b32_e32 v155, v147
	v_mov_b32_e32 v151, v148
	v_mov_b32_e32 v153, v149
	v_pk_add_f32 v[22:23], v[22:23], v[154:155]
	v_pk_add_f32 v[146:147], v[150:151], v[152:153]
	s_nop 0
	v_pk_add_f32 v[22:23], v[22:23], v[146:147]
	s_nop 0
	v_add_f32_e32 v22, v22, v23
	v_fmamk_f32 v22, v22, 0x3a800000, v205
	v_cmp_gt_f32_e32 vcc, s7, v22
	v_mul_f32_e32 v23, 0x4b800000, v22
	s_nop 0
	v_cndmask_b32_e32 v22, v22, v23, vcc
	v_rsq_f32_e32 v22, v22
	s_nop 0
	v_mul_f32_e32 v23, 0x45800000, v22
	v_cndmask_b32_e32 v23, v22, v23, vcc

; #define LAS __attribute__((address_space(3)))
; __device__ __forceinline__ unsigned pk2(float lo, float hi) { unsigned r; asm volatile("v_cvt_pk_bf16_f32 %0, %1, %2" : "=v"(r) : "v"(lo), "v"(hi)); return r; }
; #define EPI_SYNC() do { asm volatile("s_waitcnt lgkmcnt(0)" ::: "memory"); __builtin_amdgcn_s_barrier(); __builtin_amdgcn_s_barrier(); asm volatile("" ::: "memory"); } while (0)
;     __device__ __forceinline__ void operator()(f32x4 (&acc)[2][2][4][2], const Unit& u, int wr, int wc, int fr, int fq, LAS unsigned char* lds) const {
;     ...
;                 cw[e] = k < 3 ? w3[k * 2 * DFF + bj * DFF + u.b0 + c] : b3[bj * DFF + u.b0 + c];
;             }
;         }
;         EPI_SYNC();
;         const LAS float* rs = (const LAS float*)(lds + EPI_RS);
;         unsigned pq[2][2][4][2][2];
; #pragma unroll
;         for (int ai = 0; ai < 2; ++ai)
; #pragma unroll
;             for (int m = 0; m < 4; ++m) {
;                 const float r = rs[128 * ai + 64 * wr + 16 * m + fr];
; #pragma unroll
;                 for (int bj = 0; bj < 2; ++bj)
; #pragma unroll
;                     for (int n = 0; n < 2; ++n) {
;                         const f32x4 v = acc[ai][bj][m][n];
;                         pq[ai][bj][m][n][0] = r != 0.f ? pk2(v.x * r, v.y * r) : 0u;
;                         pq[ai][bj][m][n][1] = r != 0.f ? pk2(v.z * r, v.w * r) : 0u;
.LBB0_167:
	s_or_b64 exec, exec, s[0:1]
	v_lshl_add_u32 v23, v25, 2, 0
	v_add_u32_e32 v24, 0, v24
	v_add_u32_e32 v23, 0x21400, v23
	v_lshl_add_u32 v24, v144, 2, v24
	v_add_u32_e32 v146, 0x21000, v24
	s_waitcnt vmcnt(6)
	ds_write2st64_b32 v23, v248, v249 offset1:8
	s_waitcnt lgkmcnt(0)
	s_barrier
	s_barrier
	ds_read_b32 v147, v146
	v_mov_b32_e32 v23, 0
	v_mov_b32_e32 v22, 0
	s_waitcnt lgkmcnt(0)
	v_cmp_neq_f32_e32 vcc, 0, v147
	s_and_saveexec_b64 s[0:1], vcc
	s_cbranch_execz .LBB0_169
	v_mul_f32_e32 v22, v131, v147
	v_mul_f32_e32 v24, v130, v147
	v_cvt_pk_bf16_f32 v22, v24, v22

; __device__ __forceinline__ float2 twid_precise(float turns) { float s_, c_; sincospif(2.0f * turns, &s_, &c_); return make_float2(c_, s_); }
; __device__ __forceinline__ int otid(int wv) { unsigned z = 0; asm volatile("" : "+v"(z)); int t = wv * 64 + (int)__builtin_amdgcn_mbcnt_hi(~0u, __builtin_amdgcn_mbcnt_lo(~0u, z)); asm volatile("" : "+v"(t)); return t; }
; __device__ __forceinline__ int obid() { int b = blockIdx.x; asm volatile("" : "+s"(b)); return b; }
; __device__ __forceinline__ int ogrid() { int g = gridDim.x; asm volatile("" : "+s"(g)); return g; }
; __device__ __forceinline__ void ph_filtergen(KP p, int l, unsigned char* sm, int wv) {
;     ...
;     const int tid = otid(wv), wid = tid >> 6, lane = tid & 63;
;     const float* b1 = p->fb1 + l * 64; const float* f1 = p->ffr1 + l * 64;
;     const float* b2 = p->fb2 + l * 64; const float* f2 = p->ffr2 + l * 64;
;     const float* w3 = p->fw3 + (size_t)l * 65536; const float* hb = p->hbias + l * 512;
;     __syncthreads();
;     for (int i = tid; i < 33 * 64; i += 512) w1s[i] = p->fw1[l * 33 * 64 + i];
;     for (int i = tid; i < 64 * 64; i += 512) w2s[i] = p->fw2[l * 4096 + i];
;     for (int item = obid(); item < 384; item += ogrid()) {
;         const int L = item < 256 ? LP : LSQ, n0 = (item < 256 ? item : item - 256) * 64;
;         bf16_t* kf = p->X + (item < 256 ? 0 : 16777216);
;         __syncthreads();
;         {
;             const int n = n0 + lane;
;             const float w = 2.0f * (float)n / (float)L;
; #pragma unroll
;             for (int q = 0; q < 2; ++q) {
;                 const int b = wid * 2 + q;
;                 const float f = 1e-4f + (float)b * 0.9999933333333334f;
;                 const float ht = f * w, red = ht - 2.0f * rintf(0.5f * ht);
;                 const float2 cs = twid_precise(0.5f * red);
;                 zf[lane * 34 + 1 + b] = cs.x; zf[lane * 34 + 17 + b] = -cs.y;
;             }
;             if (wid == 0) zf[lane * 34] = (float)n / (float)(L - 1);
.LBB0_881:
	s_or_b64 exec, exec, s[12:13]
	v_readlane_b32 s28, v254, 0
	s_mov_b32 s32, s28
	s_cmpk_gt_i32 s32, 0x2ff
	s_cbranch_scc1 .LBB0_905
	v_readlane_b32 s13, v254, 24
	s_lshl_b32 s12, s13, 8
	s_add_u32 s8, s8, s12
	s_addc_u32 s9, s9, 0
	s_waitcnt lgkmcnt(0)
	s_add_u32 s14, s10, s12
	s_addc_u32 s15, s11, 0
	s_add_u32 s0, s0, s12
	s_addc_u32 s1, s1, 0
	s_add_u32 s16, s2, s12
	s_addc_u32 s17, s3, 0
	s_lshl_b32 s2, s13, 18
	s_add_u32 s2, s4, s2
	s_addc_u32 s3, s5, 0
	s_lshl_b32 s4, s13, 11
	s_add_u32 s10, s6, s4
	v_readlane_b32 s4, v254, 22
	v_ashrrev_i32_e32 v0, 6, v18
	v_readlane_b32 s5, v254, 23
	v_and_b32_e32 v19, 63, v18
	s_load_dwordx2 s[12:13], s[4:5], 0xf0
	v_lshlrev_b32_e32 v3, 1, v0
	s_movk_i32 s4, 0x88
	v_lshlrev_b32_e32 v2, 3, v0
	v_mad_u32_u24 v31, v19, s4, 0
	v_or_b32_e32 v5, 1, v3
	v_cvt_f32_i32_e32 v4, v3
	v_ashrrev_i32_e32 v3, 31, v2
	v_add_u32_e32 v88, v31, v2
	v_lshlrev_b64 v[2:3], 2, v[2:3]
	s_addc_u32 s11, s7, 0
	v_lshl_add_u64 v[26:27], s[0:1], 0, v[2:3]
	s_add_i32 s0, 0, 0x10800
	v_lshlrev_b32_e32 v0, 5, v0
	v_lshl_add_u32 v30, v19, 2, s0
	v_readlane_b32 s0, v254, 8
	v_mul_u32_u24_e32 v6, 0x88, v19
	v_mul_u32_u24_e32 v7, 0x7c, v19
	v_add_u32_e32 v89, s0, v0
	s_add_i32 s0, 0, 0x2200
	v_ashrrev_i32_e32 v8, 3, v18
	v_cvt_f32_i32_e32 v5, v5
	v_add3_u32 v90, v6, v7, s0
	v_readlane_b32 s0, v254, 9
	v_add3_u32 v86, v31, v7, v0
	v_lshl_add_u64 v[22:23], s[8:9], 0, v[2:3]
	v_add_u32_e32 v91, s0, v0
	v_lshrrev_b32_e32 v0, 5, v8
	s_movk_i32 s0, 0x2200
	v_lshl_add_u64 v[24:25], s[14:15], 0, v[2:3]
	v_lshl_add_u64 v[28:29], s[16:17], 0, v[2:3]
	v_mul_lo_u32 v2, v0, s0
	v_readlane_b32 s0, v254, 10
	v_mul_u32_u24_sdwa v9, v18, s87 dst_sel:DWORD dst_unused:UNUSED_PAD src0_sel:BYTE_0 src1_sel:DWORD
	s_mov_b32 s18, 0x3f7fff90
	v_mov_b32_e32 v10, 0x38d1b717
	v_add_u32_e32 v92, s0, v2
	v_lshlrev_b32_e32 v0, 7, v0
	v_readlane_b32 s0, v254, 11
	v_cmp_gt_u32_e64 s[4:5], 64, v18
	v_mad_u32_u24 v87, v19, 12, v86
	v_cmp_gt_i32_e64 s[6:7], s97, v18
	v_pk_fma_f32 v[20:21], v[4:5], s[18:19], v[10:11] op_sel_hi:[1,0,0]
	v_add3_u32 v93, v9, v0, s0
	s_branch .LBB0_884
.LBB0_883:
	s_load_dword s0, s[94:95], 0x0
	s_waitcnt lgkmcnt(0)
	s_add_i32 s32, s0, s32
	s_cmpk_gt_i32 s32, 0x2ff
	s_cbranch_scc1 .LBB0_905
.LBB0_884:
	s_lshr_b32 s28, s32, 1
	s_lshl_b32 s14, s28, 6
	s_add_i32 s15, s14, 0xffffc000
	s_cmpk_lt_i32 s28, 0x100
	s_cselect_b64 s[8:9], -1, 0
	s_and_b64 s[0:1], s[8:9], exec
	s_cselect_b32 s0, s14, s15
	v_or_b32_e32 v32, s0, v19
	v_cvt_f32_i32_e32 v0, v32
	s_cselect_b32 s14, s97, 0x2000
	v_cvt_f32_u32_e32 v2, s14
	v_mov_b32_e32 v12, 0xbf1f24be
	v_add_f32_e32 v3, v0, v0
	s_waitcnt lgkmcnt(0)
	v_div_scale_f32 v4, s[0:1], v2, v2, v3
	v_rcp_f32_e32 v5, v4
	s_barrier
	v_fma_f32 v6, -v4, v5, 1.0
	v_fmac_f32_e32 v5, v6, v5
	v_div_scale_f32 v6, vcc, v3, v2, v3
	v_mul_f32_e32 v7, v6, v5
	v_fma_f32 v8, -v4, v7, v6
	v_fmac_f32_e32 v7, v8, v5
	v_fma_f32 v4, -v4, v7, v6
	v_div_fmas_f32 v4, v4, v5, v7
	v_div_fixup_f32 v2, v4, v2, v3
	v_pk_mul_f32 v[2:3], v[20:21], v[2:3] op_sel_hi:[1,0]
	s_nop 0
	v_mul_f32_e32 v4, 0.5, v2
	v_mul_f32_e32 v5, 0.5, v3
	v_rndne_f32_e32 v4, v4
	v_rndne_f32_e32 v5, v5
	v_pk_fma_f32 v[2:3], v[4:5], -2.0, v[2:3] op_sel_hi:[1,0,1]
	s_nop 0
	v_pk_mul_f32 v[2:3], v[2:3], 0.5 op_sel_hi:[1,0]
	s_nop 0
	v_pk_add_f32 v[2:3], v[2:3], v[2:3]
	s_nop 0
	v_and_b32_e32 v5, 0x7fffffff, v3
	v_and_b32_e32 v4, 0x7fffffff, v2
	v_pk_mul_f32 v[6:7], v[4:5], 0.5 op_sel_hi:[1,0]
	v_cmp_gt_f32_e64 s[0:1], |v3|, 1.0
	v_floor_f32_e32 v9, v7
	v_floor_f32_e32 v8, v6
	v_sub_f32_e32 v9, v7, v9
	v_sub_f32_e32 v8, v6, v8
	v_min_f32_e32 v9, 0x3f7fffff, v9
	v_cmp_u_f32_e32 vcc, v7, v7
	v_min_f32_e32 v8, 0x3f7fffff, v8
	v_xor_b32_e32 v5, v5, v3
	v_cndmask_b32_e32 v9, v9, v7, vcc
	v_cmp_u_f32_e32 vcc, v6, v6
	v_xor_b32_e32 v4, v4, v2
	s_nop 0
	v_cndmask_b32_e32 v8, v8, v6, vcc
	v_pk_add_f32 v[8:9], v[8:9], v[8:9]
	v_cmp_class_f32_e32 vcc, v6, v239
	s_nop 1
	v_cndmask_b32_e64 v6, v8, 0, vcc
	v_cmp_class_f32_e32 vcc, v7, v239
	s_nop 1
	v_cndmask_b32_e64 v7, v9, 0, vcc
	v_cndmask_b32_e64 v7, |v3|, v7, s[0:1]
	v_cmp_gt_f32_e64 s[0:1], |v2|, 1.0
	v_add_f32_e32 v9, v7, v7
	v_rndne_f32_e32 v9, v9
	v_cndmask_b32_e64 v6, |v2|, v6, s[0:1]
	v_add_f32_e32 v8, v6, v6
	v_rndne_f32_e32 v8, v8
	v_pk_fma_f32 v[6:7], v[8:9], -0.5, v[6:7] op_sel_hi:[1,0,1]
	s_mov_b32 s0, 0x3e75aa41
	v_pk_mul_f32 v[10:11], v[6:7], v[6:7]
	s_nop 0
	v_pk_fma_f32 v[12:13], v[10:11], s[0:1], v[12:13] op_sel_hi:[1,0,0]
	s_mov_b32 s0, 0x40234736
	v_pk_fma_f32 v[12:13], v[10:11], v[12:13], s[0:1] op_sel_hi:[1,1,0]
	s_mov_b32 s0, 0xc0a55e0e
	v_pk_fma_f32 v[12:13], v[10:11], v[12:13], s[0:1] op_sel_hi:[1,1,0]
	v_pk_mul_f32 v[14:15], v[6:7], v[10:11]
	s_mov_b32 s0, 0x40490fdb
	v_pk_mul_f32 v[12:13], v[14:15], v[12:13]
	s_nop 0
	v_pk_fma_f32 v[6:7], v[6:7], s[0:1], v[12:13] op_sel_hi:[1,0,1]
	v_cvt_i32_f32_e32 v13, v8
	s_mov_b32 s0, 0x3d4be544
	v_mov_b32_e32 v8, 0x3e642e9d
	v_cvt_i32_f32_e32 v12, v9
	v_pk_fma_f32 v[8:9], v[10:11], s[0:1], v[8:9] op_sel_hi:[1,0,0]
	s_mov_b32 s0, 0xbfaad1da
	v_pk_fma_f32 v[8:9], v[10:11], v[8:9], s[0:1] op_sel_hi:[1,1,0]
	s_mov_b32 s0, 0x4081e0d3
	v_pk_fma_f32 v[8:9], v[10:11], v[8:9], s[0:1] op_sel_hi:[1,1,0]
	s_mov_b32 s0, 0xc09de9e6
	v_pk_fma_f32 v[8:9], v[10:11], v[8:9], s[0:1] op_sel_hi:[1,1,0]
	s_nop 0
	v_pk_fma_f32 v[8:9], v[10:11], v[8:9], 1.0 op_sel_hi:[1,1,0]
	v_and_b32_e32 v10, 1, v12
	v_and_b32_e32 v11, 1, v13
	v_lshlrev_b32_e32 v12, 30, v12
	v_lshlrev_b32_e32 v13, 30, v13
	v_cmp_eq_u32_e32 vcc, 0, v10
	v_cmp_eq_u32_e64 s[0:1], 0, v11
	v_and_b32_e32 v12, 0x80000000, v12
	v_and_b32_e32 v13, 0x80000000, v13
	v_cndmask_b32_e32 v10, v9, v7, vcc
	v_cndmask_b32_e64 v11, v8, v6, s[0:1]
	v_cndmask_b32_e64 v7, -v7, v9, vcc
	v_cndmask_b32_e64 v6, -v6, v8, s[0:1]
	v_xor_b32_e32 v7, v12, v7
	v_xor_b32_e32 v6, v13, v6
	v_cmp_class_f32_e32 vcc, v3, v242
	v_cmp_class_f32_e64 s[0:1], v2, v242
	v_xor_b32_e32 v5, v5, v10
	v_xor_b32_e32 v4, v4, v11
	v_cndmask_b32_e32 v3, v204, v7, vcc
	v_cndmask_b32_e64 v2, v204, v6, s[0:1]
	v_xor_b32_e32 v5, v5, v12
	v_xor_b32_e32 v4, v4, v13
	ds_write2_b32 v88, v2, v3 offset0:1 offset1:2
	v_mov_b32_e32 v3, 0xffc00000
	v_cndmask_b32_e64 v2, v3, -v5, vcc
	v_cndmask_b32_e64 v3, v3, -v4, s[0:1]
	ds_write2_b32 v88, v3, v2 offset0:17 offset1:18
	s_and_saveexec_b64 s[0:1], s[4:5]
	s_cbranch_execz .LBB0_886
	s_add_i32 s15, s14, -1
	v_cvt_f32_u32_e32 v2, s15
	v_div_scale_f32 v3, s[16:17], v2, v2, v0
	v_rcp_f32_e32 v4, v3
	v_div_scale_f32 v5, vcc, v0, v2, v0
	v_fma_f32 v6, -v3, v4, 1.0
	v_fmac_f32_e32 v4, v6, v4
	v_mul_f32_e32 v6, v5, v4
	v_fma_f32 v7, -v3, v6, v5
	v_fmac_f32_e32 v6, v7, v4
	v_fma_f32 v3, -v3, v6, v5
	v_div_fmas_f32 v3, v3, v4, v6
	v_div_fixup_f32 v2, v3, v2, v0
	ds_write_b32 v31, v2

; __device__ __forceinline__ void ph_filtergen(KP p, int l, unsigned char* sm, int wv) {
;     ...
;             for (int i = 0; i < 8; ++i) a[i] = b2[wid * 8 + i];
; #pragma unroll 4
;             for (int j = 0; j < 64; ++j) {
;                 const float zv = h1[lane * 65 + j];
;                 const f32x4 w0 = *(const f32x4*)(w2s + j * 64 + wid * 8), w1v = *(const f32x4*)(w2s + j * 64 + wid * 8 + 4);
;                 a[0] += zv * w0.x; a[1] += zv * w0.y; a[2] += zv * w0.z; a[3] += zv * w0.w; a[4] += zv * w1v.x; a[5] += zv * w1v.y; a[6] += zv * w1v.z; a[7] += zv * w1v.w;
;             }
; #pragma unroll
;             for (int i = 0; i < 8; ++i) h2[lane * 68 + wid * 8 + i] = sinpif(f2[wid * 8 + i] * a[i] * 0.3183098861837907f);
;         }
;         __syncthreads();
; #pragma unroll 1
;         for (int pass = 0; pass < 4; ++pass) {
.LBB0_889:
	v_add_u32_e32 v7, s15, v90
	ds_read2_b32 v[38:39], v7 offset1:1
	ds_read_b128 v[14:17], v6
	ds_read_b128 v[34:37], v6 offset:16
	s_add_i32 s15, s15, 16
	s_cmpk_eq_i32 s15, 0x100
	s_waitcnt vmcnt(1) lgkmcnt(1)
	v_pk_fma_f32 v[14:15], v[38:39], v[14:15], v[10:11] op_sel_hi:[0,1,1]
	v_pk_fma_f32 v[12:13], v[38:39], v[16:17], v[12:13] op_sel_hi:[0,1,1]
	s_waitcnt vmcnt(0) lgkmcnt(0)
	v_pk_fma_f32 v[16:17], v[38:39], v[34:35], v[2:3] op_sel_hi:[0,1,1]
	v_pk_fma_f32 v[34:35], v[38:39], v[36:37], v[4:5] op_sel_hi:[0,1,1]
	ds_read_b128 v[2:5], v6 offset:256
	ds_read_b128 v[8:11], v6 offset:272
	s_waitcnt lgkmcnt(1)
	v_pk_fma_f32 v[14:15], v[38:39], v[2:3], v[14:15] op_sel:[1,0,0]
	v_pk_fma_f32 v[12:13], v[38:39], v[4:5], v[12:13] op_sel:[1,0,0]
	s_waitcnt lgkmcnt(0)
	v_pk_fma_f32 v[16:17], v[38:39], v[8:9], v[16:17] op_sel:[1,0,0]
	v_pk_fma_f32 v[34:35], v[38:39], v[10:11], v[34:35] op_sel:[1,0,0]
	ds_read2_b32 v[36:37], v7 offset0:2 offset1:3
	ds_read_b128 v[2:5], v6 offset:512
	ds_read_b128 v[8:11], v6 offset:528
	s_waitcnt lgkmcnt(1)
	v_pk_fma_f32 v[38:39], v[36:37], v[2:3], v[14:15] op_sel_hi:[0,1,1]
	v_pk_fma_f32 v[12:13], v[36:37], v[4:5], v[12:13] op_sel_hi:[0,1,1]
	s_waitcnt lgkmcnt(0)
	v_pk_fma_f32 v[8:9], v[36:37], v[8:9], v[16:17] op_sel_hi:[0,1,1]
	ds_read_b128 v[2:5], v6 offset:768
	ds_read_b128 v[14:17], v6 offset:784
	v_pk_fma_f32 v[34:35], v[36:37], v[10:11], v[34:35] op_sel_hi:[0,1,1]
	v_add_u32_e32 v6, 0x400, v6
	s_waitcnt lgkmcnt(1)
	v_pk_fma_f32 v[10:11], v[36:37], v[2:3], v[38:39] op_sel:[1,0,0]
	v_pk_fma_f32 v[12:13], v[36:37], v[4:5], v[12:13] op_sel:[1,0,0]
	s_waitcnt lgkmcnt(0)
	v_pk_fma_f32 v[2:3], v[36:37], v[14:15], v[8:9] op_sel:[1,0,0]
	v_pk_fma_f32 v[4:5], v[36:37], v[16:17], v[34:35] op_sel:[1,0,0]
	s_cbranch_scc0 .LBB0_889
	global_load_dwordx4 v[34:37], v[28:29], off
	global_load_dwordx4 v[6:9], v[28:29], off offset:16
	s_mov_b32 s18, 0x3ea2f983
	s_and_b64 s[0:1], s[8:9], exec
	s_mov_b32 s0, 0xbf1f24be
	v_mov_b64_e32 v[14:15], s[0:1]
	s_mov_b32 s0, 0x3e642e9d
	v_mov_b64_e32 v[16:17], s[0:1]
	s_cselect_b32 s0, 0, 0x2000000
	s_add_u32 s16, s12, s0
	s_mov_b32 s36, 0x3e75aa41
	s_mov_b32 s44, 0x3d4be544
	s_mov_b32 s38, 0x40234736
	s_mov_b32 s46, 0xbfaad1da
	s_mov_b32 s40, 0xc0a55e0e
	s_mov_b32 s48, 0x4081e0d3
	s_mov_b32 s50, 0xc09de9e6
	s_mov_b32 s42, 0x40490fdb
	s_addc_u32 s17, s13, 0
	s_and_b32 s31, s32, 1
	s_lshl_b32 s31, s31, 1
	s_mov_b32 s15, s72
	s_waitcnt vmcnt(1)
	v_pk_mul_f32 v[10:11], v[10:11], v[34:35]
	s_nop 0
	v_pk_mul_f32 v[34:35], v[10:11], s[18:19] op_sel_hi:[1,0]
	v_pk_mul_f32 v[12:13], v[12:13], v[36:37]
	v_and_b32_e32 v37, 0x7fffffff, v35
	v_and_b32_e32 v36, 0x7fffffff, v34
	v_pk_mul_f32 v[10:11], v[12:13], s[18:19] op_sel_hi:[1,0]
	v_pk_mul_f32 v[38:39], v[36:37], 0.5 op_sel_hi:[1,0]
	v_and_b32_e32 v13, 0x7fffffff, v11
	v_and_b32_e32 v12, 0x7fffffff, v10
	v_floor_f32_e32 v41, v39
	v_xor_b32_e32 v33, v37, v35
	v_xor_b32_e32 v48, v36, v34
	v_pk_mul_f32 v[36:37], v[12:13], 0.5 op_sel_hi:[1,0]
	v_floor_f32_e32 v40, v38
	v_sub_f32_e32 v41, v39, v41
	v_floor_f32_e32 v43, v37
	v_sub_f32_e32 v40, v38, v40
	v_min_f32_e32 v41, 0x3f7fffff, v41
	v_cmp_u_f32_e32 vcc, v39, v39
	v_floor_f32_e32 v42, v36
	v_sub_f32_e32 v43, v37, v43
	v_min_f32_e32 v40, 0x3f7fffff, v40
	v_cndmask_b32_e32 v41, v41, v39, vcc
	v_cmp_u_f32_e32 vcc, v38, v38
	v_sub_f32_e32 v42, v36, v42
	v_min_f32_e32 v43, 0x3f7fffff, v43
	v_cndmask_b32_e32 v40, v40, v38, vcc
	v_cmp_u_f32_e32 vcc, v37, v37
	v_min_f32_e32 v42, 0x3f7fffff, v42
	v_pk_add_f32 v[40:41], v[40:41], v[40:41]
	v_cndmask_b32_e32 v43, v43, v37, vcc
	v_cmp_u_f32_e32 vcc, v36, v36
	v_cmp_gt_f32_e64 s[0:1], |v35|, 1.0
	v_xor_b32_e32 v13, v13, v11
	v_cndmask_b32_e32 v42, v42, v36, vcc
	v_cmp_class_f32_e32 vcc, v38, v239
	v_pk_add_f32 v[42:43], v[42:43], v[42:43]
	s_waitcnt vmcnt(0)
	v_pk_mul_f32 v[2:3], v[2:3], v[6:7]
	v_cndmask_b32_e64 v38, v40, 0, vcc
	v_cmp_class_f32_e32 vcc, v39, v239
	v_pk_mul_f32 v[2:3], v[2:3], s[18:19] op_sel_hi:[1,0]
	v_xor_b32_e32 v12, v12, v10
	v_cndmask_b32_e64 v39, v41, 0, vcc
	v_cmp_class_f32_e32 vcc, v36, v239
	v_and_b32_e32 v7, 0x7fffffff, v3
	v_and_b32_e32 v6, 0x7fffffff, v2
	v_cndmask_b32_e64 v40, v42, 0, vcc
	v_cmp_class_f32_e32 vcc, v37, v239
	v_cndmask_b32_e64 v37, |v35|, v39, s[0:1]
	v_cmp_gt_f32_e64 s[0:1], |v34|, 1.0
	v_cndmask_b32_e64 v41, v43, 0, vcc
	v_pk_mul_f32 v[4:5], v[4:5], v[8:9]
	v_cndmask_b32_e64 v36, |v34|, v38, s[0:1]
	v_cmp_gt_f32_e64 s[0:1], |v11|, 1.0
	v_pk_mul_f32 v[4:5], v[4:5], s[18:19] op_sel_hi:[1,0]
	s_lshl_b32 s18, s14, 1
	v_cndmask_b32_e64 v39, |v11|, v41, s[0:1]
	v_cmp_gt_f32_e64 s[0:1], |v10|, 1.0
	v_add_f32_e32 v41, v37, v37
	v_rndne_f32_e32 v41, v41
	v_cndmask_b32_e64 v38, |v10|, v40, s[0:1]
	v_add_f32_e32 v40, v36, v36
	v_rndne_f32_e32 v40, v40
	v_add_f32_e32 v42, v38, v38
	v_add_f32_e32 v43, v39, v39
	v_pk_fma_f32 v[36:37], v[40:41], -0.5, v[36:37] op_sel_hi:[1,0,1]
	v_rndne_f32_e32 v42, v42
	v_rndne_f32_e32 v43, v43
	v_cvt_i32_f32_e32 v49, v41
	v_cvt_i32_f32_e32 v50, v40
	v_pk_mul_f32 v[40:41], v[36:37], v[36:37]
	v_pk_fma_f32 v[38:39], v[42:43], -0.5, v[38:39] op_sel_hi:[1,0,1]
	v_cvt_i32_f32_e32 v51, v43
	v_cvt_i32_f32_e32 v52, v42
	v_pk_fma_f32 v[42:43], v[40:41], s[36:37], v[14:15] op_sel_hi:[1,0,0]
	v_pk_fma_f32 v[46:47], v[40:41], s[44:45], v[16:17] op_sel_hi:[1,0,0]
	v_pk_fma_f32 v[42:43], v[40:41], v[42:43], s[38:39] op_sel_hi:[1,1,0]
	v_pk_fma_f32 v[46:47], v[40:41], v[46:47], s[46:47] op_sel_hi:[1,1,0]
	v_pk_mul_f32 v[44:45], v[36:37], v[40:41]
	v_pk_fma_f32 v[42:43], v[40:41], v[42:43], s[40:41] op_sel_hi:[1,1,0]
	v_pk_fma_f32 v[46:47], v[40:41], v[46:47], s[48:49] op_sel_hi:[1,1,0]
; __device__ __forceinline__ void ph_filtergen(KP p, int l, unsigned char* sm, int wv) {
;     ...
;             for (int i = 0; i < 8; ++i) h2[lane * 68 + wid * 8 + i] = sinpif(f2[wid * 8 + i] * a[i] * 0.3183098861837907f);
	v_and_b32_e32 v53, 1, v49
	v_lshlrev_b32_e32 v49, 30, v49
	v_pk_mul_f32 v[42:43], v[44:45], v[42:43]
	v_pk_fma_f32 v[44:45], v[40:41], v[46:47], s[50:51] op_sel_hi:[1,1,0]
	v_and_b32_e32 v54, 1, v50
	v_lshlrev_b32_e32 v50, 30, v50
	v_and_b32_e32 v46, 0x80000000, v49
	v_pk_fma_f32 v[36:37], v[36:37], s[42:43], v[42:43] op_sel_hi:[1,0,1]
	v_pk_fma_f32 v[40:41], v[40:41], v[44:45], 1.0 op_sel_hi:[1,1,0]
	v_cmp_eq_u32_e32 vcc, 0, v53
	v_and_b32_e32 v47, 0x80000000, v50
	v_xor_b32_e32 v33, v33, v46
	v_cndmask_b32_e32 v37, v41, v37, vcc
	v_cmp_eq_u32_e32 vcc, 0, v54
	v_xor_b32_e32 v42, v48, v47
	v_xor_b32_e32 v33, v33, v37
	v_cndmask_b32_e32 v36, v40, v36, vcc
	v_cmp_class_f32_e32 vcc, v35, v242
	v_xor_b32_e32 v36, v42, v36
	v_cmp_gt_f32_e64 s[0:1], |v3|, 1.0
	v_cndmask_b32_e32 v35, v204, v33, vcc
	v_cmp_class_f32_e32 vcc, v34, v242
	v_and_b32_e32 v33, 1, v51
	s_nop 0
	v_cndmask_b32_e32 v34, v204, v36, vcc
	v_pk_mul_f32 v[36:37], v[38:39], v[38:39]
	v_cmp_eq_u32_e32 vcc, 0, v33
	v_pk_fma_f32 v[40:41], v[36:37], s[36:37], v[14:15] op_sel_hi:[1,0,0]
	v_pk_mul_f32 v[42:43], v[38:39], v[36:37]
	v_pk_fma_f32 v[40:41], v[36:37], v[40:41], s[38:39] op_sel_hi:[1,1,0]
	s_nop 0
	v_pk_fma_f32 v[40:41], v[36:37], v[40:41], s[40:41] op_sel_hi:[1,1,0]
	s_nop 0
	v_pk_mul_f32 v[40:41], v[42:43], v[40:41]
	s_nop 0
	v_pk_fma_f32 v[38:39], v[38:39], s[42:43], v[40:41] op_sel_hi:[1,0,1]
	v_pk_fma_f32 v[40:41], v[36:37], s[44:45], v[16:17] op_sel_hi:[1,0,0]
	s_nop 0
	v_pk_fma_f32 v[40:41], v[36:37], v[40:41], s[46:47] op_sel_hi:[1,1,0]
	s_nop 0
	v_pk_fma_f32 v[40:41], v[36:37], v[40:41], s[48:49] op_sel_hi:[1,1,0]
	s_nop 0
	v_pk_fma_f32 v[40:41], v[36:37], v[40:41], s[50:51] op_sel_hi:[1,1,0]
	s_nop 0
	v_pk_fma_f32 v[36:37], v[36:37], v[40:41], 1.0 op_sel_hi:[1,1,0]
	v_and_b32_e32 v40, 1, v52
	v_cndmask_b32_e32 v33, v37, v39, vcc
	v_lshlrev_b32_e32 v37, 30, v51
	v_cmp_eq_u32_e32 vcc, 0, v40
	v_and_b32_e32 v37, 0x80000000, v37
	v_xor_b32_e32 v13, v13, v37
	v_cndmask_b32_e32 v36, v36, v38, vcc
	v_lshlrev_b32_e32 v38, 30, v52
	v_and_b32_e32 v38, 0x80000000, v38
	v_xor_b32_e32 v13, v13, v33
	v_cmp_class_f32_e32 vcc, v11, v242
	v_xor_b32_e32 v12, v12, v38
	v_xor_b32_e32 v12, v12, v36
	v_cndmask_b32_e32 v37, v204, v13, vcc
	v_cmp_class_f32_e32 vcc, v10, v242
	v_pk_mul_f32 v[10:11], v[6:7], 0.5 op_sel_hi:[1,0]
	v_xor_b32_e32 v7, v7, v3
	v_floor_f32_e32 v13, v11
	v_cndmask_b32_e32 v36, v204, v12, vcc
	v_floor_f32_e32 v12, v10
	v_sub_f32_e32 v13, v11, v13
	v_sub_f32_e32 v12, v10, v12
	v_min_f32_e32 v13, 0x3f7fffff, v13
	v_cmp_u_f32_e32 vcc, v11, v11
	v_min_f32_e32 v12, 0x3f7fffff, v12
	ds_write_b128 v87, v[34:37] offset:25344
	v_cndmask_b32_e32 v13, v13, v11, vcc
	v_cmp_u_f32_e32 vcc, v10, v10
	v_xor_b32_e32 v6, v6, v2
	s_nop 0
	v_cndmask_b32_e32 v12, v12, v10, vcc
	v_pk_add_f32 v[12:13], v[12:13], v[12:13]
	v_cmp_class_f32_e32 vcc, v10, v239
	s_nop 1
	v_cndmask_b32_e64 v10, v12, 0, vcc
	v_cmp_class_f32_e32 vcc, v11, v239
	s_nop 1
	v_cndmask_b32_e64 v11, v13, 0, vcc
	v_cndmask_b32_e64 v11, |v3|, v11, s[0:1]
	v_cmp_gt_f32_e64 s[0:1], |v2|, 1.0
	v_add_f32_e32 v13, v11, v11
	v_rndne_f32_e32 v13, v13
	v_cndmask_b32_e64 v10, |v2|, v10, s[0:1]
	v_add_f32_e32 v12, v10, v10
	v_rndne_f32_e32 v12, v12
	v_pk_fma_f32 v[10:11], v[12:13], -0.5, v[10:11] op_sel_hi:[1,0,1]
	v_cvt_i32_f32_e32 v33, v13
	v_cvt_i32_f32_e32 v38, v12
	v_pk_mul_f32 v[12:13], v[10:11], v[10:11]
	v_cmp_gt_f32_e64 s[0:1], |v5|, 1.0
	v_pk_fma_f32 v[34:35], v[12:13], s[36:37], v[14:15] op_sel_hi:[1,0,0]
	v_pk_mul_f32 v[36:37], v[10:11], v[12:13]
	v_pk_fma_f32 v[34:35], v[12:13], v[34:35], s[38:39] op_sel_hi:[1,1,0]
	s_nop 0
	v_pk_fma_f32 v[34:35], v[12:13], v[34:35], s[40:41] op_sel_hi:[1,1,0]
	s_nop 0
	v_pk_mul_f32 v[34:35], v[36:37], v[34:35]
	s_nop 0
	v_pk_fma_f32 v[10:11], v[10:11], s[42:43], v[34:35] op_sel_hi:[1,0,1]
	v_pk_fma_f32 v[34:35], v[12:13], s[44:45], v[16:17] op_sel_hi:[1,0,0]
	s_nop 0
	v_pk_fma_f32 v[34:35], v[12:13], v[34:35], s[46:47] op_sel_hi:[1,1,0]
	s_nop 0
	v_pk_fma_f32 v[34:35], v[12:13], v[34:35], s[48:49] op_sel_hi:[1,1,0]
; __device__ __forceinline__ unsigned pk2(float lo, float hi) { unsigned r; asm volatile("v_cvt_pk_bf16_f32 %0, %1, %2" : "=v"(r) : "v"(lo), "v"(hi)); return r; }
; __device__ __forceinline__ void ph_filtergen(KP p, int l, unsigned char* sm, int wv) {
;     ...
;             for (int i = 0; i < 8; ++i) h2[lane * 68 + wid * 8 + i] = sinpif(f2[wid * 8 + i] * a[i] * 0.3183098861837907f);
;         }
;         __syncthreads();
; #pragma unroll 1
;         for (int pass = 0; pass < 4; ++pass) {
;             const int ol = tid & 255, o = pass * 256 + ol, ph0 = (tid >> 8) * 32;
;             float wcol[64];
; #pragma unroll
;             for (int j = 0; j < 64; ++j) wcol[j] = w3[j * 1024 + o];
; #pragma unroll 2
;             for (int pp = 0; pp < 32; ++pp) {
;                 const f32x4* hr = (const f32x4*)(h2 + (ph0 + pp) * 68);
;                 float acc0 = 0.f, acc1 = 0.f;
; #pragma unroll
;                 for (int j4 = 0; j4 < 16; ++j4) { const f32x4 hv = hr[j4]; acc0 += hv.x * wcol[j4 * 4] + hv.z * wcol[j4 * 4 + 2]; acc1 += hv.y * wcol[j4 * 4 + 1] + hv.w * wcol[j4 * 4 + 3]; }
;                 ot[ol * 65 + ph0 + pp] = acc0 + acc1;
;             }
;             __syncthreads();
;             for (int e = tid; e < 256 * 64; e += 512) {
;                 const int ol2 = e >> 6, pos = e & 63, o2 = pass * 256 + ol2, c = o2 & 511, n = n0 + pos;
;                 const float tt = (float)n / (float)(L - 1);
;                 const float delta = fabsf(-3.070113457325394f + (float)c * ((-15.350567286626971f + 3.070113457325394f) / 511.0f));
;                 float val = ot[ol2 * 65 + pos] * __expf(-tt * delta);
;                 bf16_t* kc = kf + (size_t)c * (2 * L);
;                 if (o2 < 512) { if (n == 0) val += hb[c]; kc[n] = (bf16_t)(pk2(val, 0.f) & 0xffffu); }
;                 else { if (n >= 1) kc[2 * L - n] = (bf16_t)(pk2(val, 0.f) & 0xffffu); else kc[L] = (bf16_t)0; }
	s_nop 0
	v_pk_fma_f32 v[34:35], v[12:13], v[34:35], s[50:51] op_sel_hi:[1,1,0]
	s_nop 0
	v_pk_fma_f32 v[12:13], v[12:13], v[34:35], 1.0 op_sel_hi:[1,1,0]
	v_and_b32_e32 v34, 1, v33
	v_and_b32_e32 v35, 1, v38
	v_cmp_eq_u32_e32 vcc, 0, v34
	s_nop 1
	v_cndmask_b32_e32 v11, v13, v11, vcc
	v_cmp_eq_u32_e32 vcc, 0, v35
	v_lshlrev_b32_e32 v13, 30, v38
	v_and_b32_e32 v13, 0x80000000, v13
	v_cndmask_b32_e32 v10, v12, v10, vcc
	v_lshlrev_b32_e32 v12, 30, v33
	v_and_b32_e32 v12, 0x80000000, v12
	v_xor_b32_e32 v7, v7, v12
	v_xor_b32_e32 v6, v6, v13
	v_xor_b32_e32 v7, v7, v11
	v_cmp_class_f32_e32 vcc, v3, v242
	v_xor_b32_e32 v6, v6, v10
	s_nop 0
	v_cndmask_b32_e32 v3, v204, v7, vcc
	v_cmp_class_f32_e32 vcc, v2, v242
	v_and_b32_e32 v7, 0x7fffffff, v5
	s_nop 0
	v_cndmask_b32_e32 v2, v204, v6, vcc
	v_and_b32_e32 v6, 0x7fffffff, v4
	v_pk_mul_f32 v[8:9], v[6:7], 0.5 op_sel_hi:[1,0]
	v_xor_b32_e32 v7, v7, v5
	v_floor_f32_e32 v11, v9
	v_floor_f32_e32 v10, v8
	v_sub_f32_e32 v11, v9, v11
	v_sub_f32_e32 v10, v8, v10
	v_min_f32_e32 v11, 0x3f7fffff, v11
	v_cmp_u_f32_e32 vcc, v9, v9
	v_min_f32_e32 v10, 0x3f7fffff, v10
	v_xor_b32_e32 v6, v6, v4
	v_cndmask_b32_e32 v11, v11, v9, vcc
	v_cmp_u_f32_e32 vcc, v8, v8
	s_nop 1
	v_cndmask_b32_e32 v10, v10, v8, vcc
	v_pk_add_f32 v[10:11], v[10:11], v[10:11]
	v_cmp_class_f32_e32 vcc, v8, v239
	s_nop 1
	v_cndmask_b32_e64 v8, v10, 0, vcc
	v_cmp_class_f32_e32 vcc, v9, v239
	s_nop 1
	v_cndmask_b32_e64 v9, v11, 0, vcc
	v_cndmask_b32_e64 v9, |v5|, v9, s[0:1]
	v_cmp_gt_f32_e64 s[0:1], |v4|, 1.0
	v_add_f32_e32 v11, v9, v9
	v_rndne_f32_e32 v11, v11
	v_cndmask_b32_e64 v8, |v4|, v8, s[0:1]
	v_add_f32_e32 v10, v8, v8
	v_rndne_f32_e32 v10, v10
	v_pk_fma_f32 v[8:9], v[10:11], -0.5, v[8:9] op_sel_hi:[1,0,1]
	v_cvt_i32_f32_e32 v33, v11
	v_cvt_i32_f32_e32 v34, v10
	v_pk_mul_f32 v[10:11], v[8:9], v[8:9]
	s_add_i32 s0, s14, -1
	v_pk_fma_f32 v[12:13], v[10:11], s[36:37], v[14:15] op_sel_hi:[1,0,0]
	v_pk_mul_f32 v[14:15], v[8:9], v[10:11]
	v_pk_fma_f32 v[12:13], v[10:11], v[12:13], s[38:39] op_sel_hi:[1,1,0]
	s_nop 0
	v_pk_fma_f32 v[12:13], v[10:11], v[12:13], s[40:41] op_sel_hi:[1,1,0]
	s_nop 0
	v_pk_mul_f32 v[12:13], v[14:15], v[12:13]
	s_nop 0
	v_pk_fma_f32 v[8:9], v[8:9], s[42:43], v[12:13] op_sel_hi:[1,0,1]
	v_pk_fma_f32 v[12:13], v[10:11], s[44:45], v[16:17] op_sel_hi:[1,0,0]
	s_nop 0
	v_pk_fma_f32 v[12:13], v[10:11], v[12:13], s[46:47] op_sel_hi:[1,1,0]
	s_nop 0
	v_pk_fma_f32 v[12:13], v[10:11], v[12:13], s[48:49] op_sel_hi:[1,1,0]
	s_nop 0
	v_pk_fma_f32 v[12:13], v[10:11], v[12:13], s[50:51] op_sel_hi:[1,1,0]
	s_nop 0
	v_pk_fma_f32 v[10:11], v[10:11], v[12:13], 1.0 op_sel_hi:[1,1,0]
	v_and_b32_e32 v12, 1, v33
	v_and_b32_e32 v13, 1, v34
	v_cmp_eq_u32_e32 vcc, 0, v12
	s_nop 1
	v_cndmask_b32_e32 v9, v11, v9, vcc
	v_cmp_eq_u32_e32 vcc, 0, v13
	v_lshlrev_b32_e32 v11, 30, v34
	v_and_b32_e32 v11, 0x80000000, v11
	v_cndmask_b32_e32 v8, v10, v8, vcc
	v_lshlrev_b32_e32 v10, 30, v33
	v_and_b32_e32 v10, 0x80000000, v10
	v_xor_b32_e32 v7, v7, v10
	v_xor_b32_e32 v6, v6, v11
	v_xor_b32_e32 v7, v7, v9
	v_cmp_class_f32_e32 vcc, v5, v242
	v_xor_b32_e32 v6, v6, v8
	v_ashrrev_i32_e32 v33, 31, v32
	v_cndmask_b32_e32 v5, v204, v7, vcc
	v_cmp_class_f32_e32 vcc, v4, v242
	s_nop 1
	v_cndmask_b32_e32 v4, v204, v6, vcc
	ds_write_b128 v87, v[2:5] offset:25360
	v_cvt_f32_u32_e32 v2, s0
	s_and_b64 s[0:1], s[8:9], exec
	s_cselect_b32 s42, 15, 14
	v_cmp_eq_u32_e64 s[8:9], 0, v32
	v_div_scale_f32 v3, s[0:1], v2, v2, -v0
	v_rcp_f32_e32 v4, v3
	v_cmp_lt_i32_e64 s[0:1], 0, v32
	s_waitcnt lgkmcnt(0)
	s_barrier
	v_fma_f32 v5, -v3, v4, 1.0
	v_fmac_f32_e32 v4, v5, v4
	v_div_scale_f32 v5, vcc, -v0, v2, -v0
	v_mul_f32_e32 v6, v5, v4
	v_fma_f32 v7, -v3, v6, v5
	v_fmac_f32_e32 v6, v7, v4
	v_fma_f32 v3, -v3, v6, v5
	v_div_fmas_f32 v3, v3, v4, v6
	v_div_fixup_f32 v94, v3, v2, -v0
	v_sub_u32_e32 v2, s18, v32
	v_ashrrev_i32_e32 v3, 31, v2
	s_branch .LBB0_892
.LBB0_891:
	s_or_b64 exec, exec, s[18:19]
	s_add_i32 s31, s31, 1
	s_bitcmp0_b32 s31, 0
	s_barrier
	s_cbranch_scc1 .LBB0_883
